# P4 second-pass LoRA items get the same fragment-row prefetch; scan staging y pass with precomputed LDS addresses and grouped row stores
# baseline (speedup 1.0000x reference)
.LBB0_955:
	s_ashr_i32 s0, s10, 1
	s_mul_hi_i32 s1, s0, 0x92492493
	s_add_i32 s1, s1, s0
	s_lshr_b32 s6, s1, 31
	s_ashr_i32 s1, s1, 8
	s_add_i32 s1, s1, s6
	s_mulk_i32 s1, 0x41
	s_add_i32 s0, s0, s1
	s_lshl_b32 s68, s0, 4
	s_addk_i32 s68, 0x410
	v_or_b32_e32 v78, s68, v169
	v_mad_i64_i32 v[102:103], s[0:1], v78, s56, v[118:119]
	global_load_dwordx4 v[244:247], v[102:103], off offset:3072
	global_load_dwordx4 v[244:247], v[102:103], off offset:3136
	global_load_dwordx4 v[244:247], v[102:103], off offset:3200
	global_load_dwordx4 v[244:247], v[102:103], off offset:3264
	global_load_dwordx4 v[244:247], v[102:103], off offset:3328
	global_load_dwordx4 v[244:247], v[102:103], off offset:3392
	global_load_dwordx4 v[244:247], v[102:103], off offset:3456
	global_load_dwordx4 v[244:247], v[102:103], off offset:3520
	global_load_dwordx4 v[244:247], v[102:103], off offset:3584
	global_load_dwordx4 v[244:247], v[102:103], off offset:-576
	global_load_dwordx4 v[244:247], v[102:103], off offset:-512
	global_load_dwordx4 v[244:247], v[102:103], off offset:-448
	global_load_dwordx4 v[244:247], v[102:103], off offset:-384
	global_load_dwordx4 v[244:247], v[102:103], off offset:-320
	global_load_dwordx4 v[244:247], v[102:103], off offset:-256
	global_load_dwordx4 v[244:247], v[102:103], off offset:-192
	global_load_dwordx4 v[244:247], v[102:103], off offset:-128
	global_load_dwordx4 v[244:247], v[102:103], off offset:-64
	global_load_dwordx4 v[74:77], v[102:103], off offset:3072
	v_mul_hi_i32 v79, v78, s35
	v_lshrrev_b32_e32 v80, 31, v79
	v_ashrrev_i32_e32 v79, 12, v79
	v_add_u32_e32 v79, v79, v80
	v_mul_i32_i24_e32 v79, 0x2010, v79
	v_sub_u32_e32 v78, v78, v79
	v_cmp_lt_i32_e32 vcc, 0, v78
	v_mov_b32_e32 v78, v111
	v_mov_b32_e32 v79, v111
	v_mov_b32_e32 v80, v111
	v_mov_b32_e32 v81, v111
	v_mov_b32_e32 v82, v111
	v_mov_b32_e32 v83, v111
	v_mov_b32_e32 v84, v111
	v_mov_b32_e32 v85, v111
	s_and_saveexec_b64 s[0:1], vcc
	s_cbranch_execz .LBB0_957
	global_load_dwordx4 v[86:89], v[102:103], off offset:-576
	s_waitcnt vmcnt(0)
	v_lshlrev_b32_e32 v85, 16, v86
	v_and_b32_e32 v84, 0xffff0000, v86
	v_lshlrev_b32_e32 v83, 16, v87
	v_and_b32_e32 v82, 0xffff0000, v87
	v_lshlrev_b32_e32 v81, 16, v88
	v_and_b32_e32 v80, 0xffff0000, v88
	v_lshlrev_b32_e32 v79, 16, v89
	v_and_b32_e32 v78, 0xffff0000, v89
